# layer-1 gate/up weight conversion (29% of the P0 weight items) deferred into layer 0's first SwiGLU GEMM epilogues, one 64x32 item per wave per tile, LDS-free (row loads per lane, 16-bit row stores)
# baseline (speedup 1.0000x reference)
; #define LAS __attribute__((address_space(3)))
; #define LDS_WAIT() asm volatile("s_waitcnt lgkmcnt(0)" ::: "memory")
; __device__ __forceinline__ unsigned pk2(float lo, float hi) { f32x2_t v = {lo, hi}; bf16x2_t b = __builtin_convertvector(v, bf16x2_t); return __builtin_bit_cast(unsigned, b); }
; __device__ __forceinline__ void tr_item(const float* W, int ldw, int k0, int n0src, bf16* WT, int ldt, int drow0, int dk0, const float* gain, LAS float* scr, int lane) {
;     { f32x4 v[8];
; #pragma unroll
;       for (int i = 0; i < 8; ++i) v[i] = *(const f32x4*)(W + (size_t)(k0 + 8 * i + (lane >> 3)) * ldw + n0src + 4 * (lane & 7));
; #pragma unroll
;       for (int i = 0; i < 8; ++i) { const int kk = 8 * i + (lane >> 3); f32x4 t = v[i]; if (gain) t = t * gain[k0 + kk];
;           LAS float* d = scr + kk * 33 + 4 * (lane & 7); d[0] = t[0]; d[1] = t[1]; d[2] = t[2]; d[3] = t[3]; } }
;     LDS_WAIT(); asm volatile("" ::: "memory");
;     const int c = lane & 7;
; #pragma unroll
;     for (int j = 0; j < 4; ++j) { const int n = (lane >> 3) + 8 * j; const LAS float* s = scr + (8 * c) * 33 + n;
;         v4u o; o.x = pk2(s[0 * 33], s[1 * 33]); o.y = pk2(s[2 * 33], s[3 * 33]); o.z = pk2(s[4 * 33], s[5 * 33]); o.w = pk2(s[6 * 33], s[7 * 33]);
;         *(v4u*)(WT + (size_t)(drow0 + n) * ldt + dk0 + 8 * c) = o; }
;     LDS_WAIT(); asm volatile("" ::: "memory");
; __device__ __forceinline__ void p0_weights(LAS unsigned char* lds, const float* const* in, unsigned char* wsW, int gw, int NGW, int wave, int lane) {
;     ...
;     for (int it = gw; it < 2 * IT_LAYER; it += NGW) {
;         const int l = it / IT_LAYER; int r = it % IT_LAYER; unsigned char* wl = wsW + (size_t)l * W_LAYER;
;         if (r < 2 * IT_GU) { const int f = r / IT_GU; r %= IT_GU; const int nblk = 2 * FF / 32, kb = r / nblk, nb = r % nblk, n0 = 32 * nb;
;             const int j0 = n0 < FF ? n0 : n0 - FF, drow = (j0 >> 7) * 256 + (n0 < FF ? 0 : 128) + (j0 & 127);
;             tr_item(in[f ? 11 : 4] + (size_t)l * DM * 2 * FF, 2 * FF, 64 * kb, n0, (bf16*)(wl + (f ? W_GU2 : W_GU1)), DM, drow, 64 * kb, nullptr, scr, lane); continue; }
.Lpw_nomul:
	ds_write_b32 v42, v0
	ds_write_b32 v42, v1 offset:4
	ds_write_b32 v42, v2 offset:8
	ds_write_b32 v42, v3 offset:12
	ds_write_b32 v42, v4 offset:1056
	ds_write_b32 v42, v5 offset:1060
	ds_write_b32 v42, v6 offset:1064
	ds_write_b32 v42, v7 offset:1068
	ds_write_b32 v42, v8 offset:2112
	ds_write_b32 v42, v9 offset:2116
	ds_write_b32 v42, v10 offset:2120
	ds_write_b32 v42, v11 offset:2124
	ds_write_b32 v42, v12 offset:3168
	ds_write_b32 v42, v13 offset:3172
	ds_write_b32 v42, v14 offset:3176
	ds_write_b32 v42, v15 offset:3180
	ds_write_b32 v42, v16 offset:4224
	ds_write_b32 v42, v17 offset:4228
	ds_write_b32 v42, v18 offset:4232
	ds_write_b32 v42, v19 offset:4236
	ds_write_b32 v42, v20 offset:5280
	ds_write_b32 v42, v21 offset:5284
	ds_write_b32 v42, v22 offset:5288
	ds_write_b32 v42, v23 offset:5292
	ds_write_b32 v42, v24 offset:6336
	ds_write_b32 v42, v25 offset:6340
	ds_write_b32 v42, v26 offset:6344
	ds_write_b32 v42, v27 offset:6348
	ds_write_b32 v42, v28 offset:7392
	ds_write_b32 v42, v29 offset:7396
	ds_write_b32 v42, v30 offset:7400
	ds_write_b32 v42, v31 offset:7404
	s_add_u32 s51, s51, s30
	s_sub_u32 s10, s51, 0x9800
	s_cmp_lt_u32 s10, 0x5800
	s_cbranch_scc0 .Lpw_keep
	s_add_u32 s51, s51, 0x5800
.Lpw_keep:
	s_cmp_lt_u32 s51, 0x13000
	s_cbranch_scc0 .Lpw_last

; __device__ __forceinline__ void p0_weights(LAS unsigned char* lds, const float* const* in, unsigned char* wsW, int gw, int NGW, int wave, int lane) {
;     ...
;     for (int it = gw; it < 2 * IT_LAYER; it += NGW) {
;         const int l = it / IT_LAYER; int r = it % IT_LAYER; unsigned char* wl = wsW + (size_t)l * W_LAYER;
;         if (r < 2 * IT_GU) { const int f = r / IT_GU; r %= IT_GU; const int nblk = 2 * FF / 32, kb = r / nblk, nb = r % nblk, n0 = 32 * nb;
;             const int j0 = n0 < FF ? n0 : n0 - FF, drow = (j0 >> 7) * 256 + (n0 < FF ? 0 : 128) + (j0 & 127);
;             tr_item(in[f ? 11 : 4] + (size_t)l * DM * 2 * FF, 2 * FF, 64 * kb, n0, (bf16*)(wl + (f ? W_GU2 : W_GU1)), DM, drow, 64 * kb, nullptr, scr, lane); continue; }
	s_cmp_ge_u32 s51, 0x9800
	s_cselect_b32 s10, 1, 0
	s_mul_i32 s11, s10, 0x9800
	s_sub_u32 s11, s51, s11
	s_mul_i32 s12, s10, 0xa000000
	s_add_u32 s66, s3, s12
	s_addc_u32 s67, s8, 0
	s_mov_b32 s69, 0
	s_cmp_lt_u32 s11, 0x5800
	s_cbranch_scc0 .Lpw_notgu_b
	s_cmp_ge_u32 s11, 0x2c00
	s_cselect_b32 s13, 1, 0
	s_cselect_b32 s60, s20, s44
	s_cselect_b32 s61, s21, s45
	s_mul_i32 s14, s13, 0x2c00
	s_sub_u32 s11, s11, s14
	s_mul_hi_u32 s15, s11, 0xba2e8c
	s_mul_i32 s14, s15, 0x160
	s_sub_u32 s16, s11, s14
	s_lshl_b32 s16, s16, 5
	s_mul_i32 s14, s10, 0x5800000
	s_add_u32 s60, s60, s14
	s_addc_u32 s61, s61, 0
	s_mul_i32 s14, s15, 0x2c0000
	s_add_u32 s60, s60, s14
	s_addc_u32 s61, s61, 0
	s_lshl_b32 s14, s16, 2
	s_add_u32 s60, s60, s14
	s_addc_u32 s61, s61, 0
	s_mov_b32 s62, 0xb000
	s_mov_b32 s63, 0x58000
	s_cmp_ge_u32 s16, 0x1600
	s_cselect_b32 s17, 1, 0
	s_mul_i32 s18, s17, 0x1600
	s_sub_u32 s18, s16, s18
	s_lshr_b32 s19, s18, 7
	s_lshl_b32 s19, s19, 8
	s_lshl_b32 s14, s17, 7
	s_add_u32 s19, s19, s14
	s_and_b32 s14, s18, 0x7f
	s_add_u32 s19, s19, s14
	s_mul_i32 s14, s13, 0x2c00000
	s_add_u32 s66, s66, s14
	s_addc_u32 s67, s67, 0
	s_lshl_b32 s14, s19, 12
	s_add_u32 s66, s66, s14
	s_addc_u32 s67, s67, 0
	s_lshl_b32 s14, s15, 7
	s_add_u32 s66, s66, s14
	s_addc_u32 s67, s67, 0
	s_movk_i32 s68, 0x1000
	s_mov_b32 s70, 0x8000
	s_branch .Lpw_pdone_b

; __device__ __forceinline__ v4u pk8(f32x4 a, f32x4 b) { v4u w; w.x = pk2(a[0], a[1]); w.y = pk2(a[2], a[3]); w.z = pk2(b[0], b[1]); w.w = pk2(b[2], b[3]); return w; }
;     __device__ __forceinline__ void operator()(const accv (&acc)[2][2][4][2], const pg8::Unit& u, int wr, int wc, int fr, int fq) const {
;         const int row0 = u.pm * 256 + wr * 64 + fr, col0 = u.pn * 128 + wc * 32 + 8 * fq;
; #pragma unroll
;         for (int ai = 0; ai < 2; ++ai)
; #pragma unroll
;             for (int m = 0; m < 4; ++m) {
;                 f32x4 a[2];
; #pragma unroll
;                 for (int n = 0; n < 2; ++n)
; #pragma unroll
;                     for (int i = 0; i < 4; ++i) { const float g = acc[ai][0][m][n][i], up = acc[ai][1][m][n][i];
;                         a[n][i] = g * __builtin_amdgcn_rcpf(1.f + __builtin_amdgcn_exp2f(-1.4426950408889634f * g)) * up; }
;                 *(v4u*)(O + (unsigned)((row0 + ai * 128 + m * 16) * FF + col0)) = pk8(a[0], a[1]);
;             }
; __device__ __forceinline__ void p0_weights(LAS unsigned char* lds, const float* const* in, unsigned char* wsW, int gw, int NGW, int wave, int lane) {
;     ...
;         if (r < 2 * IT_GU) { const int f = r / IT_GU; r %= IT_GU; const int nblk = 2 * FF / 32, kb = r / nblk, nb = r % nblk, n0 = 32 * nb;
;             const int j0 = n0 < FF ? n0 : n0 - FF, drow = (j0 >> 7) * 256 + (n0 < FF ? 0 : 128) + (j0 & 127);
;             tr_item(in[f ? 11 : 4] + (size_t)l * DM * 2 * FF, 2 * FF, 64 * kb, n0, (bf16*)(wl + (f ? W_GU2 : W_GU1)), DM, drow, 64 * kb, nullptr, scr, lane); continue; }
.LBB0_233:
	v_lshl_add_u32 v147, s78, 8, v140
	v_lshl_or_b32 v146, s14, 7, v142
	s_movk_i32 s12, 0x1600
	s_andn2_b64 vcc, exec, s[4:5]
	s_mov_b64 s[4:5], -1
	s_mov_b32 s100, 0xbfb8aa3b
	s_mov_b32 s101, 0xbfb8aa3b
	v_mad_u64_u32 v[152:153], s[14:15], v147, s12, v[146:147]
	s_cmp_lg_u32 s92, 0
	s_cbranch_scc1 .Lgu1_cv_skip_a
	v_readlane_b32 s20, v255, 24
	s_add_i32 s21, s19, -1
	s_lshl_b32 s21, s21, 11
	s_add_u32 s20, s20, s21
	s_cmp_ge_u32 s20, 0x2c00
	s_cselect_b32 s22, 1, 0
	s_mul_i32 s21, s22, 0x2c00
	s_sub_u32 s20, s20, s21
	s_mul_hi_u32 s30, s20, 0xba2e8c
	s_mul_i32 s21, s30, 0x160
	s_sub_u32 s32, s20, s21
	s_lshl_b32 s32, s32, 5
	v_readlane_b32 s80, v255, 0
	v_readlane_b32 s81, v255, 1
	s_nop 1
	s_sub_u32 s80, s80, 0x60
	s_subb_u32 s81, s81, 0
	s_mul_i32 s21, s22, 56
	s_load_dwordx2 s[82:83], s[80:81], s21
	s_mul_i32 s33, s30, 0x2c0000
	s_lshl_b32 s21, s32, 2
	s_add_u32 s33, s33, s21
	s_add_u32 s33, s33, 0x5800000
	s_cmp_ge_u32 s32, 0x1600
	s_cselect_b32 s40, 1, 0
	s_mul_i32 s21, s40, 0x1600
	s_sub_u32 s21, s32, s21
	s_lshr_b32 s42, s21, 7
	s_lshl_b32 s42, s42, 8
	s_lshl_b32 s43, s40, 7
	s_add_u32 s42, s42, s43
	s_and_b32 s21, s21, 0x7f
	s_add_u32 s42, s42, s21
	v_readlane_b32 s66, v255, 17
	v_readlane_b32 s67, v255, 18
	s_mul_i32 s21, s22, 0x2c00000
	s_add_u32 s21, s21, 0xe800000
	s_nop 0
	s_add_u32 s66, s66, s21
	s_addc_u32 s67, s67, 0
	s_lshl_b32 s21, s42, 12
	s_add_u32 s66, s66, s21
	s_addc_u32 s67, s67, 0
	s_lshl_b32 s21, s30, 7
	s_add_u32 s66, s66, s21
	s_addc_u32 s67, s67, 0
	v_mbcnt_lo_u32_b32 v211, -1, 0
	v_mbcnt_hi_u32_b32 v211, -1, v211
	v_mul_u32_u24_e32 v210, 0xb000, v211
	v_lshlrev_b32_e32 v211, 1, v211
	s_waitcnt lgkmcnt(0)
	s_add_u32 s82, s82, s33
	s_addc_u32 s83, s83, 0
	global_load_dwordx4 v[178:181], v210, s[82:83]
	global_load_dwordx4 v[182:185], v210, s[82:83] offset:16
	global_load_dwordx4 v[186:189], v210, s[82:83] offset:32
	global_load_dwordx4 v[190:193], v210, s[82:83] offset:48
	global_load_dwordx4 v[194:197], v210, s[82:83] offset:64
	global_load_dwordx4 v[198:201], v210, s[82:83] offset:80
	global_load_dwordx4 v[202:205], v210, s[82:83] offset:96
	global_load_dwordx4 v[206:209], v210, s[82:83] offset:112
.Lgu1_cv_skip_a:
	v_pk_mul_f32 v[144:145], v[124:125], s[100:101] op_sel_hi:[1,0]
	v_pk_mul_f32 v[146:147], v[126:127], s[100:101] op_sel_hi:[1,0]
	v_pk_mul_f32 v[148:149], v[120:121], s[100:101] op_sel_hi:[1,0]
	v_pk_mul_f32 v[150:151], v[122:123], s[100:101] op_sel_hi:[1,0]
	v_exp_f32_e32 v144, v144
	v_exp_f32_e32 v145, v145
	v_exp_f32_e32 v146, v146
	v_exp_f32_e32 v147, v147
	v_exp_f32_e32 v148, v148
	v_exp_f32_e32 v149, v149
	v_exp_f32_e32 v150, v150
	v_exp_f32_e32 v151, v151
	v_pk_add_f32 v[144:145], v[144:145], 1.0 op_sel_hi:[1,0]
	v_pk_add_f32 v[146:147], v[146:147], 1.0 op_sel_hi:[1,0]
	v_pk_add_f32 v[148:149], v[148:149], 1.0 op_sel_hi:[1,0]
	v_pk_add_f32 v[150:151], v[150:151], 1.0 op_sel_hi:[1,0]
	v_rcp_f32_e32 v144, v144
	v_rcp_f32_e32 v145, v145
	v_rcp_f32_e32 v146, v146
	v_rcp_f32_e32 v147, v147
	v_rcp_f32_e32 v148, v148
	v_rcp_f32_e32 v149, v149
	v_rcp_f32_e32 v150, v150
	v_rcp_f32_e32 v151, v151
	v_pk_mul_f32 v[124:125], v[124:125], v[144:145]
	v_pk_mul_f32 v[126:127], v[126:127], v[146:147]
	v_pk_mul_f32 v[120:121], v[120:121], v[148:149]
	v_pk_mul_f32 v[122:123], v[122:123], v[150:151]
	v_mov_b32_e32 v168, v152
	v_pk_mul_f32 v[124:125], v[124:125], v[116:117]
	v_pk_mul_f32 v[126:127], v[126:127], v[118:119]
	v_pk_mul_f32 v[120:121], v[120:121], v[112:113]
	v_pk_mul_f32 v[122:123], v[122:123], v[114:115]
	v_lshl_add_u64 v[154:155], v[168:169], 1, s[64:65]
	v_cvt_pk_bf16_f32 v112, v124, v125
	v_cvt_pk_bf16_f32 v113, v126, v127
	v_cvt_pk_bf16_f32 v114, v120, v121
	v_cvt_pk_bf16_f32 v115, v122, v123
	global_store_dwordx4 v[154:155], v[112:115], off
	v_pk_mul_f32 v[144:145], v[108:109], s[100:101] op_sel_hi:[1,0]
	v_pk_mul_f32 v[146:147], v[110:111], s[100:101] op_sel_hi:[1,0]
	v_pk_mul_f32 v[148:149], v[104:105], s[100:101] op_sel_hi:[1,0]
	v_pk_mul_f32 v[150:151], v[106:107], s[100:101] op_sel_hi:[1,0]
	v_exp_f32_e32 v144, v144
	v_exp_f32_e32 v145, v145
	v_exp_f32_e32 v146, v146
	v_exp_f32_e32 v147, v147
	v_exp_f32_e32 v148, v148
	v_exp_f32_e32 v149, v149
	v_exp_f32_e32 v150, v150
	v_exp_f32_e32 v151, v151
	v_pk_add_f32 v[144:145], v[144:145], 1.0 op_sel_hi:[1,0]
	v_pk_add_f32 v[146:147], v[146:147], 1.0 op_sel_hi:[1,0]
	v_pk_add_f32 v[148:149], v[148:149], 1.0 op_sel_hi:[1,0]
	v_pk_add_f32 v[150:151], v[150:151], 1.0 op_sel_hi:[1,0]
	v_rcp_f32_e32 v144, v144
	v_rcp_f32_e32 v145, v145
	v_rcp_f32_e32 v146, v146
	v_rcp_f32_e32 v147, v147
	v_rcp_f32_e32 v148, v148
	v_rcp_f32_e32 v149, v149
	v_rcp_f32_e32 v150, v150
	v_rcp_f32_e32 v151, v151
	v_pk_mul_f32 v[108:109], v[108:109], v[144:145]
	v_pk_mul_f32 v[110:111], v[110:111], v[146:147]
	v_pk_mul_f32 v[104:105], v[104:105], v[148:149]
	v_pk_mul_f32 v[106:107], v[106:107], v[150:151]
	v_add_u32_e32 v168, 0x16000, v152
	v_pk_mul_f32 v[108:109], v[108:109], v[100:101]
	v_pk_mul_f32 v[110:111], v[110:111], v[102:103]
	v_pk_mul_f32 v[104:105], v[104:105], v[96:97]
	v_pk_mul_f32 v[106:107], v[106:107], v[98:99]
	v_lshl_add_u64 v[154:155], v[168:169], 1, s[64:65]
	v_cvt_pk_bf16_f32 v96, v108, v109
	v_cvt_pk_bf16_f32 v97, v110, v111
	v_cvt_pk_bf16_f32 v98, v104, v105
	v_cvt_pk_bf16_f32 v99, v106, v107
	global_store_dwordx4 v[154:155], v[96:99], off
	v_pk_mul_f32 v[144:145], v[92:93], s[100:101] op_sel_hi:[1,0]
	v_pk_mul_f32 v[146:147], v[94:95], s[100:101] op_sel_hi:[1,0]
	v_pk_mul_f32 v[148:149], v[88:89], s[100:101] op_sel_hi:[1,0]
	v_pk_mul_f32 v[150:151], v[90:91], s[100:101] op_sel_hi:[1,0]
	v_exp_f32_e32 v144, v144
	v_exp_f32_e32 v145, v145
; __device__ __forceinline__ v4u pk8(f32x4 a, f32x4 b) { v4u w; w.x = pk2(a[0], a[1]); w.y = pk2(a[2], a[3]); w.z = pk2(b[0], b[1]); w.w = pk2(b[2], b[3]); return w; }
;     __device__ __forceinline__ void operator()(const accv (&acc)[2][2][4][2], const pg8::Unit& u, int wr, int wc, int fr, int fq) const {
;     ...
;         for (int ai = 0; ai < 2; ++ai)
; #pragma unroll
;             for (int m = 0; m < 4; ++m) {
;                 f32x4 a[2];
; #pragma unroll
;                 for (int n = 0; n < 2; ++n)
; #pragma unroll
;                     for (int i = 0; i < 4; ++i) { const float g = acc[ai][0][m][n][i], up = acc[ai][1][m][n][i];
;                         a[n][i] = g * __builtin_amdgcn_rcpf(1.f + __builtin_amdgcn_exp2f(-1.4426950408889634f * g)) * up; }
;                 *(v4u*)(O + (unsigned)((row0 + ai * 128 + m * 16) * FF + col0)) = pk8(a[0], a[1]);
;             }
	v_exp_f32_e32 v146, v146
	v_exp_f32_e32 v147, v147
	v_exp_f32_e32 v148, v148
	v_exp_f32_e32 v149, v149
	v_exp_f32_e32 v150, v150
	v_exp_f32_e32 v151, v151
	v_pk_add_f32 v[144:145], v[144:145], 1.0 op_sel_hi:[1,0]
	v_pk_add_f32 v[146:147], v[146:147], 1.0 op_sel_hi:[1,0]
	v_pk_add_f32 v[148:149], v[148:149], 1.0 op_sel_hi:[1,0]
	v_pk_add_f32 v[150:151], v[150:151], 1.0 op_sel_hi:[1,0]
	v_rcp_f32_e32 v144, v144
	v_rcp_f32_e32 v145, v145
	v_rcp_f32_e32 v146, v146
	v_rcp_f32_e32 v147, v147
	v_rcp_f32_e32 v148, v148
	v_rcp_f32_e32 v149, v149
	v_rcp_f32_e32 v150, v150
	v_rcp_f32_e32 v151, v151
	v_pk_mul_f32 v[92:93], v[92:93], v[144:145]
	v_pk_mul_f32 v[94:95], v[94:95], v[146:147]
	v_pk_mul_f32 v[88:89], v[88:89], v[148:149]
	v_pk_mul_f32 v[90:91], v[90:91], v[150:151]
	v_add_u32_e32 v168, 0x2c000, v152
	v_pk_mul_f32 v[92:93], v[92:93], v[84:85]
	v_pk_mul_f32 v[94:95], v[94:95], v[86:87]
	v_pk_mul_f32 v[88:89], v[88:89], v[80:81]
	v_pk_mul_f32 v[90:91], v[90:91], v[82:83]
	v_lshl_add_u64 v[154:155], v[168:169], 1, s[64:65]
	v_cvt_pk_bf16_f32 v80, v92, v93
	v_cvt_pk_bf16_f32 v81, v94, v95
	v_cvt_pk_bf16_f32 v82, v88, v89
	v_cvt_pk_bf16_f32 v83, v90, v91
	global_store_dwordx4 v[154:155], v[80:83], off
	v_pk_mul_f32 v[144:145], v[76:77], s[100:101] op_sel_hi:[1,0]
	v_pk_mul_f32 v[146:147], v[78:79], s[100:101] op_sel_hi:[1,0]
	v_pk_mul_f32 v[148:149], v[72:73], s[100:101] op_sel_hi:[1,0]
	v_pk_mul_f32 v[150:151], v[74:75], s[100:101] op_sel_hi:[1,0]
	v_exp_f32_e32 v144, v144
	v_exp_f32_e32 v145, v145
	v_exp_f32_e32 v146, v146
	v_exp_f32_e32 v147, v147
	v_exp_f32_e32 v148, v148
	v_exp_f32_e32 v149, v149
	v_exp_f32_e32 v150, v150
	v_exp_f32_e32 v151, v151
	v_pk_add_f32 v[144:145], v[144:145], 1.0 op_sel_hi:[1,0]
	v_pk_add_f32 v[146:147], v[146:147], 1.0 op_sel_hi:[1,0]
	v_pk_add_f32 v[148:149], v[148:149], 1.0 op_sel_hi:[1,0]
	v_pk_add_f32 v[150:151], v[150:151], 1.0 op_sel_hi:[1,0]
	v_rcp_f32_e32 v144, v144
	v_rcp_f32_e32 v145, v145
	v_rcp_f32_e32 v146, v146
	v_rcp_f32_e32 v147, v147
	v_rcp_f32_e32 v148, v148
	v_rcp_f32_e32 v149, v149
	v_rcp_f32_e32 v150, v150
	v_rcp_f32_e32 v151, v151
	v_pk_mul_f32 v[76:77], v[76:77], v[144:145]
	v_pk_mul_f32 v[78:79], v[78:79], v[146:147]
	v_pk_mul_f32 v[72:73], v[72:73], v[148:149]
	v_pk_mul_f32 v[74:75], v[74:75], v[150:151]
	v_add_u32_e32 v168, 0x42000, v152
	v_pk_mul_f32 v[76:77], v[76:77], v[68:69]
	v_pk_mul_f32 v[78:79], v[78:79], v[70:71]
	v_pk_mul_f32 v[72:73], v[72:73], v[64:65]
	v_pk_mul_f32 v[74:75], v[74:75], v[66:67]
	v_lshl_add_u64 v[154:155], v[168:169], 1, s[64:65]
	v_cvt_pk_bf16_f32 v64, v76, v77
	v_cvt_pk_bf16_f32 v65, v78, v79
	v_cvt_pk_bf16_f32 v66, v72, v73
	v_cvt_pk_bf16_f32 v67, v74, v75
	global_store_dwordx4 v[154:155], v[64:67], off
	v_pk_mul_f32 v[144:145], v[60:61], s[100:101] op_sel_hi:[1,0]
	v_pk_mul_f32 v[146:147], v[62:63], s[100:101] op_sel_hi:[1,0]
	v_pk_mul_f32 v[148:149], v[56:57], s[100:101] op_sel_hi:[1,0]
	v_pk_mul_f32 v[150:151], v[58:59], s[100:101] op_sel_hi:[1,0]
	v_exp_f32_e32 v144, v144
	v_exp_f32_e32 v145, v145
	v_exp_f32_e32 v146, v146
	v_exp_f32_e32 v147, v147
	v_exp_f32_e32 v148, v148
	v_exp_f32_e32 v149, v149
	v_exp_f32_e32 v150, v150
	v_exp_f32_e32 v151, v151
	v_pk_add_f32 v[144:145], v[144:145], 1.0 op_sel_hi:[1,0]
	v_pk_add_f32 v[146:147], v[146:147], 1.0 op_sel_hi:[1,0]
	v_pk_add_f32 v[148:149], v[148:149], 1.0 op_sel_hi:[1,0]
	v_pk_add_f32 v[150:151], v[150:151], 1.0 op_sel_hi:[1,0]
	v_rcp_f32_e32 v144, v144
	v_rcp_f32_e32 v145, v145
	v_rcp_f32_e32 v146, v146
	v_rcp_f32_e32 v147, v147
	v_rcp_f32_e32 v148, v148
	v_rcp_f32_e32 v149, v149
	v_rcp_f32_e32 v150, v150
	v_rcp_f32_e32 v151, v151
	v_pk_mul_f32 v[60:61], v[60:61], v[144:145]
	v_pk_mul_f32 v[62:63], v[62:63], v[146:147]
	v_pk_mul_f32 v[56:57], v[56:57], v[148:149]
	v_pk_mul_f32 v[58:59], v[58:59], v[150:151]
	v_add_u32_e32 v168, 0xb0000, v152
	v_pk_mul_f32 v[60:61], v[60:61], v[52:53]
	v_pk_mul_f32 v[62:63], v[62:63], v[54:55]
	v_pk_mul_f32 v[56:57], v[56:57], v[48:49]
	v_pk_mul_f32 v[58:59], v[58:59], v[50:51]
	v_lshl_add_u64 v[154:155], v[168:169], 1, s[64:65]
	v_cvt_pk_bf16_f32 v48, v60, v61
	v_cvt_pk_bf16_f32 v49, v62, v63
	v_cvt_pk_bf16_f32 v50, v56, v57
	v_cvt_pk_bf16_f32 v51, v58, v59
	global_store_dwordx4 v[154:155], v[48:51], off
	v_pk_mul_f32 v[144:145], v[44:45], s[100:101] op_sel_hi:[1,0]
	v_pk_mul_f32 v[146:147], v[46:47], s[100:101] op_sel_hi:[1,0]
	v_pk_mul_f32 v[148:149], v[40:41], s[100:101] op_sel_hi:[1,0]
	v_pk_mul_f32 v[150:151], v[42:43], s[100:101] op_sel_hi:[1,0]
	v_exp_f32_e32 v144, v144
	v_exp_f32_e32 v145, v145
	v_exp_f32_e32 v146, v146
	v_exp_f32_e32 v147, v147
	v_exp_f32_e32 v148, v148
	v_exp_f32_e32 v149, v149
	v_exp_f32_e32 v150, v150
	v_exp_f32_e32 v151, v151
	v_pk_add_f32 v[144:145], v[144:145], 1.0 op_sel_hi:[1,0]
	v_pk_add_f32 v[146:147], v[146:147], 1.0 op_sel_hi:[1,0]
	v_pk_add_f32 v[148:149], v[148:149], 1.0 op_sel_hi:[1,0]
	v_pk_add_f32 v[150:151], v[150:151], 1.0 op_sel_hi:[1,0]
	v_rcp_f32_e32 v144, v144
	v_rcp_f32_e32 v145, v145
	v_rcp_f32_e32 v146, v146
	v_rcp_f32_e32 v147, v147
	v_rcp_f32_e32 v148, v148
	v_rcp_f32_e32 v149, v149
	v_rcp_f32_e32 v150, v150
	v_rcp_f32_e32 v151, v151
	v_pk_mul_f32 v[44:45], v[44:45], v[144:145]
	v_pk_mul_f32 v[46:47], v[46:47], v[146:147]
	v_pk_mul_f32 v[40:41], v[40:41], v[148:149]
	v_pk_mul_f32 v[42:43], v[42:43], v[150:151]
	v_add_u32_e32 v168, 0xc6000, v152
	v_pk_mul_f32 v[44:45], v[44:45], v[36:37]
	v_pk_mul_f32 v[46:47], v[46:47], v[38:39]
	v_pk_mul_f32 v[40:41], v[40:41], v[32:33]
	v_pk_mul_f32 v[42:43], v[42:43], v[34:35]
	v_lshl_add_u64 v[154:155], v[168:169], 1, s[64:65]
	v_cvt_pk_bf16_f32 v32, v44, v45
; #define LAS __attribute__((address_space(3)))
; #define LDS_WAIT() asm volatile("s_waitcnt lgkmcnt(0)" ::: "memory")
; __device__ __forceinline__ unsigned pk2(float lo, float hi) { f32x2_t v = {lo, hi}; bf16x2_t b = __builtin_convertvector(v, bf16x2_t); return __builtin_bit_cast(unsigned, b); }
; __device__ __forceinline__ v4u pk8(f32x4 a, f32x4 b) { v4u w; w.x = pk2(a[0], a[1]); w.y = pk2(a[2], a[3]); w.z = pk2(b[0], b[1]); w.w = pk2(b[2], b[3]); return w; }
;     __device__ __forceinline__ void operator()(const accv (&acc)[2][2][4][2], const pg8::Unit& u, int wr, int wc, int fr, int fq) const {
;     ...
;                     for (int i = 0; i < 4; ++i) { const float g = acc[ai][0][m][n][i], up = acc[ai][1][m][n][i];
;                         a[n][i] = g * __builtin_amdgcn_rcpf(1.f + __builtin_amdgcn_exp2f(-1.4426950408889634f * g)) * up; }
;                 *(v4u*)(O + (unsigned)((row0 + ai * 128 + m * 16) * FF + col0)) = pk8(a[0], a[1]);
;             }
; __device__ __forceinline__ void tr_item(const float* W, int ldw, int k0, int n0src, bf16* WT, int ldt, int drow0, int dk0, const float* gain, LAS float* scr, int lane) {
;     ...
;       for (int i = 0; i < 8; ++i) { const int kk = 8 * i + (lane >> 3); f32x4 t = v[i]; if (gain) t = t * gain[k0 + kk];
;           LAS float* d = scr + kk * 33 + 4 * (lane & 7); d[0] = t[0]; d[1] = t[1]; d[2] = t[2]; d[3] = t[3]; } }
;     LDS_WAIT(); asm volatile("" ::: "memory");
;     const int c = lane & 7;
; #pragma unroll
;     for (int j = 0; j < 4; ++j) { const int n = (lane >> 3) + 8 * j; const LAS float* s = scr + (8 * c) * 33 + n;
;         v4u o; o.x = pk2(s[0 * 33], s[1 * 33]); o.y = pk2(s[2 * 33], s[3 * 33]); o.z = pk2(s[4 * 33], s[5 * 33]); o.w = pk2(s[6 * 33], s[7 * 33]);
;         *(v4u*)(WT + (size_t)(drow0 + n) * ldt + dk0 + 8 * c) = o; }
	v_cvt_pk_bf16_f32 v33, v46, v47
	v_cvt_pk_bf16_f32 v34, v40, v41
	v_cvt_pk_bf16_f32 v35, v42, v43
	global_store_dwordx4 v[154:155], v[32:35], off
	v_pk_mul_f32 v[144:145], v[28:29], s[100:101] op_sel_hi:[1,0]
	v_pk_mul_f32 v[146:147], v[30:31], s[100:101] op_sel_hi:[1,0]
	v_pk_mul_f32 v[148:149], v[24:25], s[100:101] op_sel_hi:[1,0]
	v_pk_mul_f32 v[150:151], v[26:27], s[100:101] op_sel_hi:[1,0]
	v_exp_f32_e32 v144, v144
	v_exp_f32_e32 v145, v145
	v_exp_f32_e32 v146, v146
	v_exp_f32_e32 v147, v147
	v_exp_f32_e32 v148, v148
	v_exp_f32_e32 v149, v149
	v_exp_f32_e32 v150, v150
	v_exp_f32_e32 v151, v151
	v_pk_add_f32 v[144:145], v[144:145], 1.0 op_sel_hi:[1,0]
	v_pk_add_f32 v[146:147], v[146:147], 1.0 op_sel_hi:[1,0]
	v_pk_add_f32 v[148:149], v[148:149], 1.0 op_sel_hi:[1,0]
	v_pk_add_f32 v[150:151], v[150:151], 1.0 op_sel_hi:[1,0]
	v_rcp_f32_e32 v144, v144
	v_rcp_f32_e32 v145, v145
	v_rcp_f32_e32 v146, v146
	v_rcp_f32_e32 v147, v147
	v_rcp_f32_e32 v148, v148
	v_rcp_f32_e32 v149, v149
	v_rcp_f32_e32 v150, v150
	v_rcp_f32_e32 v151, v151
	v_pk_mul_f32 v[28:29], v[28:29], v[144:145]
	v_pk_mul_f32 v[30:31], v[30:31], v[146:147]
	v_pk_mul_f32 v[24:25], v[24:25], v[148:149]
	v_pk_mul_f32 v[26:27], v[26:27], v[150:151]
	v_add_u32_e32 v168, 0xdc000, v152
	v_pk_mul_f32 v[28:29], v[28:29], v[20:21]
	v_pk_mul_f32 v[30:31], v[30:31], v[22:23]
	v_pk_mul_f32 v[24:25], v[24:25], v[16:17]
	v_pk_mul_f32 v[26:27], v[26:27], v[18:19]
	v_lshl_add_u64 v[154:155], v[168:169], 1, s[64:65]
	v_cvt_pk_bf16_f32 v16, v28, v29
	v_cvt_pk_bf16_f32 v17, v30, v31
	v_cvt_pk_bf16_f32 v18, v24, v25
	v_cvt_pk_bf16_f32 v19, v26, v27
	global_store_dwordx4 v[154:155], v[16:19], off
	v_pk_mul_f32 v[144:145], v[12:13], s[100:101] op_sel_hi:[1,0]
	v_pk_mul_f32 v[146:147], v[14:15], s[100:101] op_sel_hi:[1,0]
	v_pk_mul_f32 v[148:149], v[8:9], s[100:101] op_sel_hi:[1,0]
	v_pk_mul_f32 v[150:151], v[10:11], s[100:101] op_sel_hi:[1,0]
	v_exp_f32_e32 v144, v144
	v_exp_f32_e32 v145, v145
	v_exp_f32_e32 v146, v146
	v_exp_f32_e32 v147, v147
	v_exp_f32_e32 v148, v148
	v_exp_f32_e32 v149, v149
	v_exp_f32_e32 v150, v150
	v_exp_f32_e32 v151, v151
	v_pk_add_f32 v[144:145], v[144:145], 1.0 op_sel_hi:[1,0]
	v_pk_add_f32 v[146:147], v[146:147], 1.0 op_sel_hi:[1,0]
	v_pk_add_f32 v[148:149], v[148:149], 1.0 op_sel_hi:[1,0]
	v_pk_add_f32 v[150:151], v[150:151], 1.0 op_sel_hi:[1,0]
	v_rcp_f32_e32 v144, v144
	v_rcp_f32_e32 v145, v145
	v_rcp_f32_e32 v146, v146
	v_rcp_f32_e32 v147, v147
	v_rcp_f32_e32 v148, v148
	v_rcp_f32_e32 v149, v149
	v_rcp_f32_e32 v150, v150
	v_rcp_f32_e32 v151, v151
	v_pk_mul_f32 v[12:13], v[12:13], v[144:145]
	v_pk_mul_f32 v[14:15], v[14:15], v[146:147]
	v_pk_mul_f32 v[8:9], v[8:9], v[148:149]
	v_pk_mul_f32 v[10:11], v[10:11], v[150:151]
	v_add_u32_e32 v168, 0xf2000, v152
	v_pk_mul_f32 v[12:13], v[12:13], v[4:5]
	v_pk_mul_f32 v[14:15], v[14:15], v[6:7]
	v_pk_mul_f32 v[8:9], v[8:9], v[0:1]
	v_pk_mul_f32 v[10:11], v[10:11], v[2:3]
	v_lshl_add_u64 v[154:155], v[168:169], 1, s[64:65]
	v_cvt_pk_bf16_f32 v0, v12, v13
	v_cvt_pk_bf16_f32 v1, v14, v15
	v_cvt_pk_bf16_f32 v2, v8, v9
	v_cvt_pk_bf16_f32 v3, v10, v11
	global_store_dwordx4 v[154:155], v[0:3], off
	s_cmp_lg_u32 s92, 0
	s_cbranch_scc1 .Lgu1_cv_skip_b
	s_waitcnt vmcnt(8)
	v_cvt_pk_bf16_f32 v212, v178, v179
	global_store_short v211, v212, s[66:67]
	s_add_u32 s66, s66, 0x1000
	s_addc_u32 s67, s67, 0
	global_store_short_d16_hi v211, v212, s[66:67]
	s_add_u32 s66, s66, 0x1000
	s_addc_u32 s67, s67, 0
	v_cvt_pk_bf16_f32 v213, v180, v181
	global_store_short v211, v213, s[66:67]
	s_add_u32 s66, s66, 0x1000
	s_addc_u32 s67, s67, 0
	global_store_short_d16_hi v211, v213, s[66:67]
	s_add_u32 s66, s66, 0x1000
	s_addc_u32 s67, s67, 0
	v_cvt_pk_bf16_f32 v212, v182, v183
	global_store_short v211, v212, s[66:67]
	s_add_u32 s66, s66, 0x1000
	s_addc_u32 s67, s67, 0
	global_store_short_d16_hi v211, v212, s[66:67]
	s_add_u32 s66, s66, 0x1000
	s_addc_u32 s67, s67, 0
	v_cvt_pk_bf16_f32 v213, v184, v185
	global_store_short v211, v213, s[66:67]
	s_add_u32 s66, s66, 0x1000
	s_addc_u32 s67, s67, 0
	global_store_short_d16_hi v211, v213, s[66:67]
	s_add_u32 s66, s66, 0x1000
	s_addc_u32 s67, s67, 0
	v_cvt_pk_bf16_f32 v212, v186, v187
	global_store_short v211, v212, s[66:67]
	s_add_u32 s66, s66, 0x1000
	s_addc_u32 s67, s67, 0
	global_store_short_d16_hi v211, v212, s[66:67]
	s_add_u32 s66, s66, 0x1000
	s_addc_u32 s67, s67, 0
	v_cvt_pk_bf16_f32 v213, v188, v189
	global_store_short v211, v213, s[66:67]
	s_add_u32 s66, s66, 0x1000
	s_addc_u32 s67, s67, 0
	global_store_short_d16_hi v211, v213, s[66:67]
	s_add_u32 s66, s66, 0x1000
	s_addc_u32 s67, s67, 0
	v_cvt_pk_bf16_f32 v212, v190, v191
	global_store_short v211, v212, s[66:67]
	s_add_u32 s66, s66, 0x1000
	s_addc_u32 s67, s67, 0
	global_store_short_d16_hi v211, v212, s[66:67]
	s_add_u32 s66, s66, 0x1000
	s_addc_u32 s67, s67, 0
	v_cvt_pk_bf16_f32 v213, v192, v193
	global_store_short v211, v213, s[66:67]
	s_add_u32 s66, s66, 0x1000
	s_addc_u32 s67, s67, 0
	global_store_short_d16_hi v211, v213, s[66:67]
	s_add_u32 s66, s66, 0x1000
	s_addc_u32 s67, s67, 0
	v_cvt_pk_bf16_f32 v212, v194, v195
	global_store_short v211, v212, s[66:67]
	s_add_u32 s66, s66, 0x1000
	s_addc_u32 s67, s67, 0
	global_store_short_d16_hi v211, v212, s[66:67]
	s_add_u32 s66, s66, 0x1000
	s_addc_u32 s67, s67, 0
	v_cvt_pk_bf16_f32 v213, v196, v197
	global_store_short v211, v213, s[66:67]
	s_add_u32 s66, s66, 0x1000
	s_addc_u32 s67, s67, 0
	global_store_short_d16_hi v211, v213, s[66:67]
	s_add_u32 s66, s66, 0x1000
	s_addc_u32 s67, s67, 0
	v_cvt_pk_bf16_f32 v212, v198, v199
	global_store_short v211, v212, s[66:67]
	s_add_u32 s66, s66, 0x1000
	s_addc_u32 s67, s67, 0
	global_store_short_d16_hi v211, v212, s[66:67]
	s_add_u32 s66, s66, 0x1000
	s_addc_u32 s67, s67, 0
	v_cvt_pk_bf16_f32 v213, v200, v201
	global_store_short v211, v213, s[66:67]
	s_add_u32 s66, s66, 0x1000
	s_addc_u32 s67, s67, 0
	global_store_short_d16_hi v211, v213, s[66:67]
	s_add_u32 s66, s66, 0x1000
	s_addc_u32 s67, s67, 0
	v_cvt_pk_bf16_f32 v212, v202, v203
	global_store_short v211, v212, s[66:67]
	s_add_u32 s66, s66, 0x1000
	s_addc_u32 s67, s67, 0
	global_store_short_d16_hi v211, v212, s[66:67]
	s_add_u32 s66, s66, 0x1000
	s_addc_u32 s67, s67, 0
	v_cvt_pk_bf16_f32 v213, v204, v205
	global_store_short v211, v213, s[66:67]
	s_add_u32 s66, s66, 0x1000
	s_addc_u32 s67, s67, 0
	global_store_short_d16_hi v211, v213, s[66:67]
	s_add_u32 s66, s66, 0x1000
	s_addc_u32 s67, s67, 0
	v_cvt_pk_bf16_f32 v212, v206, v207
	global_store_short v211, v212, s[66:67]
	s_add_u32 s66, s66, 0x1000
	s_addc_u32 s67, s67, 0
	global_store_short_d16_hi v211, v212, s[66:67]
	s_add_u32 s66, s66, 0x1000
	s_addc_u32 s67, s67, 0
	v_cvt_pk_bf16_f32 v213, v208, v209
	global_store_short v211, v213, s[66:67]
	s_add_u32 s66, s66, 0x1000
	s_addc_u32 s67, s67, 0
	global_store_short_d16_hi v211, v213, s[66:67]
	s_add_u32 s66, s66, 0x1000
	s_addc_u32 s67, s67, 0
.Lgu1_cv_skip_b:
	s_cbranch_vccnz .LBB0_226
	s_andn2_b64 vcc, exec, s[6:7]
	s_cbranch_vccnz .LBB0_225
	s_barrier
	s_branch .LBB0_225
